# combo2: combo1 + layer-1 norm loop: next-row prefetch waited at the latch with a counted vmcnt(3) instead of vmcnt(0) at the header (no store drain per row)
# speedup vs baseline: 1.0333x; 1.0099x over previous
; template <bool FG, bool BIN = false> __device__ __forceinline__ void norm_phase(const float* hin, const float* gain, bf16_t* out, const float* win, const float* fbias, float* logf, int gw, int NGW, int lane) {
;     float g[16];
; #pragma unroll
;     for (int i = 0; i < 2; ++i) { const int c0 = 8 * (lane + 64 * i); const f32x4 a = *(const f32x4*)(gain + c0), b = *(const f32x4*)(gain + c0 + 4);
;         g[8 * i + 0] = a[0]; g[8 * i + 1] = a[1]; g[8 * i + 2] = a[2]; g[8 * i + 3] = a[3]; g[8 * i + 4] = b[0]; g[8 * i + 5] = b[1]; g[8 * i + 6] = b[2]; g[8 * i + 7] = b[3]; }
;     float wf[6][16]; float fb[6];
;     if (FG) {
; #pragma unroll
;         for (int i = 0; i < 2; ++i)
; #pragma unroll
;             for (int e = 0; e < 8; ++e) { const float* wp = win + (size_t)(8 * (lane + 64 * i) + e) * INC + 2432;
; #pragma unroll
;                 for (int j = 0; j < 6; ++j) wf[j][8 * i + e] = wp[j] * g[8 * i + e]; }
; #pragma unroll
;         for (int j = 0; j < 6; ++j) fb[j] = fbias[j];
;     }
;     f32x4 nx[4];
;     const bf16_t* hbin = (const bf16_t*)hin;
;     ...
;     if (gw < T) NORM_LD(gw);
.LBB0_1105:
	s_or_b64 exec, exec, s[4:5]
	s_mov_b32 s0, -1
	s_waitcnt lgkmcnt(0)
	s_barrier
	s_mov_b32 s2, -1
	v_mbcnt_lo_u32_b32 v0, s0, 0
	v_mbcnt_hi_u32_b32 v24, s0, v0
	s_mov_b64 s[0:1], s[46:47]
	s_mov_b64 s[6:7], s[46:47]
	s_mov_b64 s[14:15], s[46:47]
	s_mov_b64 s[8:9], s[46:47]
	s_mov_b64 s[16:17], s[46:47]
	s_mov_b64 s[4:5], s[46:47]
	s_cmpk_gt_i32 s48, 0x7fff
	s_cbranch_scc1 .LBB0_1112
	s_load_dwordx2 s[10:11], s[6:7], 0x10
	s_load_dwordx2 s[12:13], s[8:9], 0x18
	v_lshlrev_b32_e32 v16, 3, v24
	s_movk_i32 s3, 0x3818
	s_movk_i32 s20, 0x2000
	s_waitcnt lgkmcnt(0)
	s_add_u32 s18, s10, 0x1000
	s_addc_u32 s19, s11, 0
	s_add_u32 s6, s12, 0xe06000
	s_addc_u32 s7, s13, 0
	v_mov_b64_e32 v[18:19], s[6:7]
	v_mad_i64_i32 v[4:5], s[6:7], v16, s3, v[18:19]
	s_mov_b64 s[12:13], 0x2600
	v_ashrrev_i32_e32 v17, 31, v16
	v_lshl_add_u64 v[6:7], v[4:5], 0, s[12:13]
	v_add_co_u32_e32 v4, vcc, s20, v4
	v_lshl_add_u64 v[8:9], v[16:17], 2, s[18:19]
	s_nop 0
	v_addc_co_u32_e32 v5, vcc, 0, v5, vcc
	global_load_dwordx4 v[0:3], v[8:9], off
	global_load_dwordx4 v[20:23], v[4:5], off offset:1536
	global_load_dwordx2 v[38:39], v[6:7], off offset:16
	v_or_b32_e32 v4, 1, v16
	v_mad_i64_i32 v[4:5], s[6:7], v4, s3, v[18:19]
	v_lshl_add_u64 v[6:7], v[4:5], 0, s[12:13]
	v_add_co_u32_e32 v4, vcc, s20, v4
	v_add_u32_e32 v44, 0x200, v16
	s_nop 0
	v_addc_co_u32_e32 v5, vcc, 0, v5, vcc
	global_load_dwordx4 v[26:29], v[4:5], off offset:1536
	global_load_dwordx2 v[40:41], v[6:7], off offset:16
	v_or_b32_e32 v4, 2, v16
	v_mad_i64_i32 v[4:5], s[6:7], v4, s3, v[18:19]
	v_lshl_add_u64 v[6:7], v[4:5], 0, s[12:13]
	v_add_co_u32_e32 v4, vcc, s20, v4
	v_or_b32_e32 v48, 4, v16
	s_nop 0
	v_addc_co_u32_e32 v5, vcc, 0, v5, vcc
	global_load_dwordx4 v[30:33], v[4:5], off offset:1536
	global_load_dwordx2 v[42:43], v[6:7], off offset:16
	v_or_b32_e32 v4, 3, v16
	v_mad_i64_i32 v[4:5], s[6:7], v4, s3, v[18:19]
	v_add_co_u32_e32 v6, vcc, s20, v4
	v_lshl_add_u64 v[10:11], v[4:5], 0, s[12:13]
	s_nop 0
	v_addc_co_u32_e32 v7, vcc, 0, v5, vcc
	global_load_dwordx4 v[34:37], v[6:7], off offset:1536
	global_load_dwordx2 v[68:69], v[10:11], off offset:16
	s_nop 0
	global_load_dwordx4 v[4:7], v[8:9], off offset:16
	s_load_dwordx2 s[8:9], s[0:1], 0x98
	s_load_dwordx2 s[6:7], s[14:15], 0x98
	s_load_dwordx2 s[10:11], s[16:17], 0x38
	v_ashrrev_i32_e32 v45, 31, v44
	v_mad_i64_i32 v[70:71], s[0:1], v48, s3, v[18:19]
	v_lshl_add_u64 v[46:47], v[44:45], 2, s[18:19]
	global_load_dwordx4 v[8:11], v[46:47], off offset:16
	global_load_dwordx4 v[12:15], v[46:47], off
	v_lshl_add_u64 v[72:73], v[70:71], 0, s[12:13]
	s_ashr_i32 s49, s48, 31
	v_mov_b32_e32 v25, 0
	s_mul_i32 s24, s48, 24
	v_cmp_eq_u32_e64 s[14:15], 1, v24
	v_cmp_eq_u32_e64 s[16:17], 2, v24
	v_cmp_eq_u32_e64 s[18:19], 3, v24
	v_cmp_eq_u32_e64 s[22:23], 5, v24
	s_mov_b32 s26, 0xbfb8aa3b
	s_mov_b32 s27, 0xb2a5705f
	s_mov_b32 s28, 0x42ce8ed0
	s_mov_b32 s29, 0xc2b17218
	s_mov_b32 s30, 0x7f800000
	s_mov_b32 s31, 0x3f2aaaab
	s_mov_b32 s33, 0x3f317218
	s_mov_b32 s34, 0x33800000
	s_waitcnt vmcnt(10)
	v_mul_f32_e32 v45, v0, v20
	v_add_co_u32_e32 v20, vcc, s20, v70
	v_mul_f32_e32 v46, v0, v21
	s_nop 0
	v_addc_co_u32_e32 v21, vcc, 0, v71, vcc
	v_mul_f32_e32 v47, v0, v22
	v_mul_f32_e32 v48, v0, v23
	s_waitcnt vmcnt(9)
	v_mul_f32_e32 v49, v0, v38
	v_mul_f32_e32 v50, v0, v39
	s_waitcnt vmcnt(8)
	v_mul_f32_e32 v51, v1, v26
	v_mul_f32_e32 v52, v1, v27
	v_mul_f32_e32 v53, v1, v28
	v_mul_f32_e32 v54, v1, v29
	global_load_dwordx4 v[26:29], v[20:21], off offset:1536
	global_load_dwordx2 v[22:23], v[72:73], off offset:16
	v_or_b32_e32 v20, 5, v16
	v_mad_i64_i32 v[20:21], s[0:1], v20, s3, v[18:19]
	s_waitcnt vmcnt(9)
	v_mul_f32_e32 v55, v1, v40
	v_mul_f32_e32 v56, v1, v41
	s_waitcnt vmcnt(8)
	v_mul_f32_e32 v57, v2, v30
	v_mul_f32_e32 v58, v2, v31
	v_mul_f32_e32 v59, v2, v32
	v_mul_f32_e32 v60, v2, v33
	s_waitcnt vmcnt(7)
	v_mul_f32_e32 v61, v2, v42
	v_mul_f32_e32 v62, v2, v43
	s_waitcnt vmcnt(6)
	v_mul_f32_e32 v63, v3, v34
	v_mul_f32_e32 v64, v3, v35
	v_lshl_add_u64 v[34:35], v[20:21], 0, s[12:13]
	v_add_co_u32_e32 v20, vcc, s20, v20
	v_mul_f32_e32 v65, v3, v36
	s_nop 0
	v_addc_co_u32_e32 v21, vcc, 0, v21, vcc
	global_load_dwordx4 v[30:33], v[20:21], off offset:1536
	global_load_dwordx2 v[42:43], v[34:35], off offset:16
	v_or_b32_e32 v20, 6, v16
	v_mad_i64_i32 v[20:21], s[0:1], v20, s3, v[18:19]
	v_lshl_add_u64 v[38:39], v[20:21], 0, s[12:13]
	v_add_co_u32_e32 v20, vcc, s20, v20
	v_mul_f32_e32 v66, v3, v37
	s_nop 0
	v_addc_co_u32_e32 v21, vcc, 0, v21, vcc
	global_load_dwordx4 v[34:37], v[20:21], off offset:1536
	global_load_dwordx2 v[86:87], v[38:39], off offset:16
	v_or_b32_e32 v20, 7, v16
	v_mad_i64_i32 v[20:21], s[0:1], v20, s3, v[18:19]
	v_lshl_add_u64 v[70:71], v[20:21], 0, s[12:13]
	v_add_co_u32_e32 v20, vcc, s20, v20
	s_waitcnt vmcnt(9)
	v_mul_f32_e32 v67, v3, v68
	v_addc_co_u32_e32 v21, vcc, 0, v21, vcc
	global_load_dwordx4 v[38:41], v[20:21], off offset:1536
	global_load_dwordx2 v[92:93], v[70:71], off offset:16
	v_mad_i64_i32 v[20:21], s[0:1], v44, s3, v[18:19]
	v_lshl_add_u64 v[70:71], v[20:21], 0, s[12:13]
	v_add_co_u32_e32 v20, vcc, s20, v20
	v_mul_f32_e32 v68, v3, v69
	s_nop 0
	v_addc_co_u32_e32 v21, vcc, 0, v21, vcc
	global_load_dwordx4 v[94:97], v[20:21], off offset:1536
	global_load_dwordx2 v[98:99], v[70:71], off offset:16
	v_add_u32_e32 v20, 0x201, v16
	v_mad_i64_i32 v[20:21], s[0:1], v20, s3, v[18:19]
	v_lshl_add_u64 v[70:71], v[20:21], 0, s[12:13]
	v_add_co_u32_e32 v20, vcc, s20, v20
	s_waitcnt vmcnt(9)
; template <bool FG, bool BIN = false> __device__ __forceinline__ void norm_phase(const float* hin, const float* gain, bf16_t* out, const float* win, const float* fbias, float* logf, int gw, int NGW, int lane) {
;     ...
;             for (int e = 0; e < 8; ++e) { const float* wp = win + (size_t)(8 * (lane + 64 * i) + e) * INC + 2432;
; #pragma unroll
;                 for (int j = 0; j < 6; ++j) wf[j][8 * i + e] = wp[j] * g[8 * i + e]; }
; #pragma unroll
;         for (int j = 0; j < 6; ++j) fb[j] = fbias[j];
;     }
;     f32x4 nx[4];
;     const bf16_t* hbin = (const bf16_t*)hin;
;     ...
;     if (gw < T) NORM_LD(gw);
	v_mul_f32_e32 v69, v4, v26
	v_addc_co_u32_e32 v21, vcc, 0, v21, vcc
	global_load_dwordx4 v[100:103], v[20:21], off offset:1536
	global_load_dwordx2 v[104:105], v[70:71], off offset:16
	v_add_u32_e32 v20, 0x202, v16
	v_mad_i64_i32 v[20:21], s[0:1], v20, s3, v[18:19]
	v_lshl_add_u64 v[70:71], v[20:21], 0, s[12:13]
	v_add_co_u32_e32 v20, vcc, s20, v20
	v_mul_f32_e32 v72, v4, v29
	s_nop 0
	v_addc_co_u32_e32 v21, vcc, 0, v21, vcc
	global_load_dwordx4 v[106:109], v[20:21], off offset:1536
	global_load_dwordx2 v[110:111], v[70:71], off offset:16
	v_add_u32_e32 v20, 0x203, v16
	v_mad_i64_i32 v[20:21], s[0:1], v20, s3, v[18:19]
	v_lshl_add_u64 v[70:71], v[20:21], 0, s[12:13]
	v_add_co_u32_e32 v20, vcc, s20, v20
	s_waitcnt vmcnt(12)
	v_mul_f32_e32 v73, v4, v22
	v_addc_co_u32_e32 v21, vcc, 0, v21, vcc
	global_load_dwordx4 v[112:115], v[20:21], off offset:1536
	global_load_dwordx2 v[116:117], v[70:71], off offset:16
	v_add_u32_e32 v20, 0x204, v16
	v_mad_i64_i32 v[20:21], s[0:1], v20, s3, v[18:19]
	v_lshl_add_u64 v[70:71], v[20:21], 0, s[12:13]
	v_add_co_u32_e32 v20, vcc, s20, v20
	v_mul_f32_e32 v74, v4, v23
	s_nop 0
	v_addc_co_u32_e32 v21, vcc, 0, v21, vcc
	global_load_dwordx4 v[118:121], v[20:21], off offset:1536
	global_load_dwordx2 v[122:123], v[70:71], off offset:16
	v_add_u32_e32 v20, 0x205, v16
	v_mad_i64_i32 v[20:21], s[0:1], v20, s3, v[18:19]
	v_lshl_add_u64 v[70:71], v[20:21], 0, s[12:13]
	v_add_co_u32_e32 v20, vcc, s20, v20
	s_waitcnt vmcnt(13)
	v_mul_f32_e32 v81, v6, v34
	v_addc_co_u32_e32 v21, vcc, 0, v21, vcc
	global_load_dwordx4 v[124:127], v[20:21], off offset:1536
	global_load_dwordx2 v[128:129], v[70:71], off offset:16
	v_add_u32_e32 v20, 0x206, v16
	v_mad_i64_i32 v[20:21], s[0:1], v20, s3, v[18:19]
	v_lshl_add_u64 v[70:71], v[20:21], 0, s[12:13]
	v_add_co_u32_e32 v20, vcc, s20, v20
	v_mul_f32_e32 v82, v6, v35
	s_nop 0
	v_addc_co_u32_e32 v21, vcc, 0, v21, vcc
	global_load_dwordx4 v[130:133], v[20:21], off offset:1536
	global_load_dwordx2 v[134:135], v[70:71], off offset:16
	v_add_u32_e32 v20, 0x207, v16
	v_mad_i64_i32 v[18:19], s[0:1], v20, s3, v[18:19]
	v_lshl_add_u64 v[20:21], v[18:19], 0, s[12:13]
	v_add_co_u32_e32 v18, vcc, s20, v18
	s_lshl_b64 s[0:1], s[48:49], 11
	s_nop 0
	v_addc_co_u32_e32 v19, vcc, 0, v19, vcc
	s_waitcnt lgkmcnt(0)
	s_add_u32 s12, s8, s0
	global_load_dwordx4 v[136:139], v[18:19], off offset:1536
	global_load_dwordx2 v[140:141], v[20:21], off offset:16
	s_addc_u32 s13, s9, s1
	v_lshlrev_b64 v[20:21], 1, v[16:17]
	v_lshl_add_u64 v[16:17], s[12:13], 0, v[20:21]
	s_mov_b32 s3, 0x18484000
	v_add_co_u32_e32 v18, vcc, s3, v16
	s_mov_b64 s[12:13], 0x18484000
	s_nop 0
	v_addc_co_u32_e32 v19, vcc, 0, v17, vcc
	v_lshl_add_u64 v[16:17], v[16:17], 0, s[12:13]
	global_load_dwordx4 v[142:145], v[18:19], off
	v_mul_f32_e32 v70, v4, v27
	v_mul_f32_e32 v71, v4, v28
	global_load_dwordx4 v[26:29], v[16:17], off offset:1024
	s_nop 0
	global_load_dwordx4 v[16:19], v25, s[10:11] offset:24
	global_load_dwordx2 v[22:23], v25, s[10:11] offset:40
	s_load_dwordx2 s[4:5], s[4:5], 0x98
	s_mul_hi_i32 s3, s48, 24
	v_ashrrev_i32_e32 v25, 31, v24
	v_cmp_gt_i32_e64 s[10:11], 6, v24
	v_cmp_eq_u32_e64 s[12:13], 0, v24
	s_waitcnt lgkmcnt(0)
	s_add_u32 s4, s4, s24
	s_addc_u32 s5, s5, s3
	v_cmp_eq_u32_e64 s[20:21], 4, v24
	v_lshl_add_u64 v[24:25], v[24:25], 2, s[4:5]
	s_mov_b64 s[4:5], 0x17804000
	s_ashr_i32 s59, s58, 31
	v_lshl_add_u64 v[24:25], v[24:25], 0, s[4:5]
	s_add_u32 s4, s6, s0
	s_addc_u32 s5, s7, s1
	s_add_i32 s0, s48, s58
	s_ashr_i32 s1, s0, 31
	s_lshl_b64 s[6:7], s[58:59], 11
	s_lshl_b64 s[0:1], s[0:1], 11
	s_add_u32 s8, s8, s0
	v_mul_f32_e32 v75, v5, v30
	v_mul_f32_e32 v76, v5, v31
	v_mul_f32_e32 v77, v5, v32
	v_mul_f32_e32 v78, v5, v33
	v_mul_f32_e32 v79, v5, v42
	v_mul_f32_e32 v80, v5, v43
	v_mul_f32_e32 v83, v6, v36
	v_mul_f32_e32 v84, v6, v37
	s_waitcnt vmcnt(22)
	v_mul_f32_e32 v85, v6, v86
	v_mul_f32_e32 v86, v6, v87
	s_waitcnt vmcnt(21)
	v_mul_f32_e32 v87, v7, v38
	v_mul_f32_e32 v88, v7, v39
	v_mul_f32_e32 v89, v7, v40
	v_mul_f32_e32 v90, v7, v41
	s_waitcnt vmcnt(20)
	v_mul_f32_e32 v91, v7, v92
	v_mul_f32_e32 v92, v7, v93
	s_waitcnt vmcnt(19)
	v_mul_f32_e32 v93, v12, v94
	v_mul_f32_e32 v94, v12, v95
	v_mul_f32_e32 v95, v12, v96
	v_mul_f32_e32 v96, v12, v97
	s_waitcnt vmcnt(18)
	v_mul_f32_e32 v97, v12, v98
	v_mul_f32_e32 v98, v12, v99
	s_waitcnt vmcnt(17)
	v_mul_f32_e32 v99, v13, v100
	v_mul_f32_e32 v100, v13, v101
	v_mul_f32_e32 v101, v13, v102
	v_mul_f32_e32 v102, v13, v103
	s_waitcnt vmcnt(16)
	v_mul_f32_e32 v103, v13, v104
	v_mul_f32_e32 v104, v13, v105
	s_waitcnt vmcnt(15)
	v_mul_f32_e32 v105, v14, v106
	v_mul_f32_e32 v106, v14, v107
	v_mul_f32_e32 v107, v14, v108
	v_mul_f32_e32 v108, v14, v109
	s_waitcnt vmcnt(14)
	v_mul_f32_e32 v109, v14, v110
	v_mul_f32_e32 v110, v14, v111
	s_waitcnt vmcnt(13)
	v_mul_f32_e32 v111, v15, v112
	v_mul_f32_e32 v112, v15, v113
	v_mul_f32_e32 v113, v15, v114
	v_mul_f32_e32 v114, v15, v115
	s_waitcnt vmcnt(12)
	v_mul_f32_e32 v115, v15, v116
	v_mul_f32_e32 v116, v15, v117
	s_waitcnt vmcnt(11)
	v_mul_f32_e32 v117, v8, v118
	v_mul_f32_e32 v118, v8, v119
	v_mul_f32_e32 v119, v8, v120
	v_mul_f32_e32 v120, v8, v121
	s_waitcnt vmcnt(10)
	v_mul_f32_e32 v121, v8, v122
	v_mul_f32_e32 v122, v8, v123
	s_waitcnt vmcnt(9)
	v_mul_f32_e32 v123, v9, v124
	v_mul_f32_e32 v124, v9, v125
	v_mul_f32_e32 v125, v9, v126
	v_mul_f32_e32 v126, v9, v127
	s_waitcnt vmcnt(8)
	v_mul_f32_e32 v127, v9, v128
	v_mul_f32_e32 v128, v9, v129
	s_waitcnt vmcnt(7)
	v_mul_f32_e32 v129, v10, v130
	v_mul_f32_e32 v130, v10, v131
	v_mul_f32_e32 v131, v10, v132
	v_mul_f32_e32 v132, v10, v133
	s_waitcnt vmcnt(6)
	v_mul_f32_e32 v133, v10, v134
	v_mul_f32_e32 v134, v10, v135
	s_waitcnt vmcnt(5)
	v_mul_f32_e32 v135, v11, v136
	s_waitcnt vmcnt(2)
	v_lshlrev_b32_e32 v34, 16, v26
	v_and_b32_e32 v35, 0xffff0000, v26
	v_mul_f32_e32 v136, v11, v137
	v_mul_f32_e32 v137, v11, v138
	v_mul_f32_e32 v138, v11, v139
	v_mul_f32_e32 v139, v11, v140
	v_mul_f32_e32 v140, v11, v141
	v_lshlrev_b32_e32 v42, 16, v142
	v_and_b32_e32 v43, 0xffff0000, v142
	v_lshlrev_b32_e32 v40, 16, v143
	v_and_b32_e32 v41, 0xffff0000, v143
	v_lshlrev_b32_e32 v38, 16, v144
	v_and_b32_e32 v39, 0xffff0000, v144
	v_lshlrev_b32_e32 v36, 16, v145
	v_and_b32_e32 v37, 0xffff0000, v145
	v_lshlrev_b32_e32 v32, 16, v27
	v_and_b32_e32 v33, 0xffff0000, v27
	v_lshlrev_b32_e32 v30, 16, v28
	v_and_b32_e32 v31, 0xffff0000, v28
	v_lshlrev_b32_e32 v28, 16, v29
	v_and_b32_e32 v29, 0xffff0000, v29
	s_addc_u32 s9, s9, s1
	v_mov_b32_e32 v141, 0x358637bd
	s_mov_b32 s3, 0x5804000
	v_mov_b32_e32 v142, 0x3ecc95a3
	v_mov_b32_e32 v143, 0x7f800000
	v_mov_b32_e32 v26, 0x3f317218
	s_waitcnt vmcnt(0)
	s_branch .LBB0_1108
; template <bool FG, bool BIN = false> __device__ __forceinline__ void norm_phase(const float* hin, const float* gain, bf16_t* out, const float* win, const float* fbias, float* logf, int gw, int NGW, int lane) {
;     ...
;     for (int row = gw; row < T; row += NGW) {
;         float x[16];
; #pragma unroll
;         for (int i = 0; i < 4; ++i) { x[4 * i + 0] = nx[i][0]; x[4 * i + 1] = nx[i][1]; x[4 * i + 2] = nx[i][2]; x[4 * i + 3] = nx[i][3]; }
;         if (row + NGW < T) NORM_LD(row + NGW);
.LBB0_1107:
	s_or_b64 exec, exec, s[0:1]
	s_and_b64 vcc, exec, s[24:25]
	s_cbranch_vccnz .Lnorm1_nonext
	s_waitcnt vmcnt(3)
	v_lshlrev_b32_e32 v144, 16, v148
	v_and_b32_e32 v145, 0xffff0000, v148
	v_lshlrev_b32_e32 v146, 16, v149
	v_and_b32_e32 v147, 0xffff0000, v149
	v_lshlrev_b32_e32 v148, 16, v150
	v_and_b32_e32 v149, 0xffff0000, v150
	v_lshlrev_b32_e32 v150, 16, v151
	v_and_b32_e32 v151, 0xffff0000, v151
	v_lshlrev_b32_e32 v152, 16, v156
	v_and_b32_e32 v153, 0xffff0000, v156
	v_lshlrev_b32_e32 v154, 16, v157
	v_and_b32_e32 v155, 0xffff0000, v157
	v_lshlrev_b32_e32 v156, 16, v158
	v_and_b32_e32 v157, 0xffff0000, v158
	v_lshlrev_b32_e32 v158, 16, v159
	v_and_b32_e32 v159, 0xffff0000, v159
.Lnorm1_nonext:
	s_add_u32 s4, s4, s6
	s_addc_u32 s5, s5, s7
	s_add_u32 s8, s8, s6
	v_lshl_add_u64 v[24:25], v[24:25], 0, s[40:41]
	s_addc_u32 s9, s9, s7
	s_andn2_b64 vcc, exec, s[24:25]
	v_mov_b32_e32 v30, v156
	v_mov_b32_e32 v31, v157
	v_mov_b32_e32 v28, v158
	v_mov_b32_e32 v29, v159
	v_mov_b32_e32 v34, v152
	v_mov_b32_e32 v35, v153
	v_mov_b32_e32 v32, v154
	v_mov_b32_e32 v33, v155
	v_mov_b32_e32 v38, v148
	v_mov_b32_e32 v39, v149
	v_mov_b32_e32 v36, v150
	v_mov_b32_e32 v37, v151
	v_mov_b32_e32 v42, v144
	v_mov_b32_e32 v43, v145
	v_mov_b32_e32 v40, v146
	v_mov_b32_e32 v41, v147
	s_cbranch_vccz .LBB0_1112

; __device__ __forceinline__ unsigned pk2(float lo, float hi) { f32x2_t v = {lo, hi}; bf16x2_t b = __builtin_convertvector(v, bf16x2_t); return __builtin_bit_cast(unsigned, b); }
; __device__ __forceinline__ float wave_sum(float v) { return xor32_sum(xor16_sum(row16_sum(v))); }
; __device__ __forceinline__ float fast_rsq(float x) { return __builtin_amdgcn_rsqf(x); }
; template <bool FG, bool BIN = false> __device__ __forceinline__ void norm_phase(const float* hin, const float* gain, bf16_t* out, const float* win, const float* fbias, float* logf, int gw, int NGW, int lane) {
;     ...
;         float ss = 0.f;
; #pragma unroll
;         for (int e = 0; e < 16; ++e) ss += x[e] * x[e];
;         ss = wave_sum(ss);
;         const float rstd = fast_rsq(ss * (1.0f / DM) + EPS);
; #pragma unroll
;         for (int i = 0; i < 2; ++i) { u32x4 w;
;             w.x = pk2(x[8 * i + 0] * rstd * g[8 * i + 0], x[8 * i + 1] * rstd * g[8 * i + 1]); w.y = pk2(x[8 * i + 2] * rstd * g[8 * i + 2], x[8 * i + 3] * rstd * g[8 * i + 3]);
;             w.z = pk2(x[8 * i + 4] * rstd * g[8 * i + 4], x[8 * i + 5] * rstd * g[8 * i + 5]); w.w = pk2(x[8 * i + 6] * rstd * g[8 * i + 6], x[8 * i + 7] * rstd * g[8 * i + 7]);
;             *(u32x4*)(out + (size_t)row * DM + 8 * (lane + 64 * i)) = w; }
;         if (FG) {
;             float mine = 0.f;
; #pragma unroll
;             for (int j = 0; j < 6; ++j) { float d = 0.f;
; #pragma unroll
;                 for (int e = 0; e < 16; ++e) d += x[e] * wf[j][e];
;                 d = wave_sum(d) * rstd + fb[j];
.LBB0_1110:
	v_mul_f32_e32 v27, v43, v43
	v_fmac_f32_e32 v27, v42, v42
	v_fmac_f32_e32 v27, v40, v40
	v_fmac_f32_e32 v27, v41, v41
	v_fmac_f32_e32 v27, v38, v38
	v_fmac_f32_e32 v27, v39, v39
	v_fmac_f32_e32 v27, v36, v36
	v_fmac_f32_e32 v27, v37, v37
	v_fmac_f32_e32 v27, v34, v34
	v_fmac_f32_e32 v27, v35, v35
	v_fmac_f32_e32 v27, v32, v32
	v_fmac_f32_e32 v27, v33, v33
	v_fmac_f32_e32 v27, v30, v30
	v_fmac_f32_e32 v27, v31, v31
	v_fmac_f32_e32 v27, v28, v28
	v_fmac_f32_e32 v27, v29, v29
	s_nop 1
	v_add_f32_dpp v27, v27, v27 quad_perm:[1,0,3,2] row_mask:0xf bank_mask:0xf bound_ctrl:1
	s_nop 1
	v_add_f32_dpp v27, v27, v27 quad_perm:[2,3,0,1] row_mask:0xf bank_mask:0xf bound_ctrl:1
	s_nop 1
	v_add_f32_dpp v27, v27, v27 row_half_mirror row_mask:0xf bank_mask:0xf bound_ctrl:1
	s_nop 1
	v_add_f32_dpp v27, v27, v27 row_mirror row_mask:0xf bank_mask:0xf bound_ctrl:1
	v_mov_b32_e32 v44, v27
	s_nop 1
	v_permlane16_swap_b32_e32 v27, v44
	v_add_f32_e32 v27, v27, v44
	v_mov_b32_e32 v44, v27
	s_nop 1
	v_permlane32_swap_b32_e32 v27, v44
	v_add_f32_e32 v27, v27, v44
	v_fmamk_f32 v27, v27, 0x3a800000, v141
	v_rsq_f32_e32 v44, v27
	v_fma_f32 v27, v45, v42, 0
	v_fmac_f32_e32 v27, v51, v43
	v_fmac_f32_e32 v27, v57, v40
	v_pk_mul_f32 v[160:161], v[42:43], v[44:45] op_sel_hi:[1,0]
	v_pk_mul_f32 v[162:163], v[40:41], v[44:45] op_sel_hi:[1,0]
	v_pk_mul_f32 v[160:161], v[0:1], v[160:161]
	v_pk_mul_f32 v[162:163], v[2:3], v[162:163]
	v_cvt_pk_bf16_f32 v160, v160, v161
	v_cvt_pk_bf16_f32 v161, v162, v163
	v_pk_mul_f32 v[162:163], v[38:39], v[44:45] op_sel_hi:[1,0]
	v_pk_mul_f32 v[164:165], v[36:37], v[44:45] op_sel_hi:[1,0]
	v_pk_mul_f32 v[162:163], v[4:5], v[162:163]
	v_pk_mul_f32 v[164:165], v[6:7], v[164:165]
	v_cvt_pk_bf16_f32 v162, v162, v163
	v_cvt_pk_bf16_f32 v163, v164, v165
	v_lshl_add_u64 v[164:165], s[4:5], 0, v[20:21]
	v_add_co_u32_e32 v164, vcc, s3, v164
	v_pk_mul_f32 v[166:167], v[28:29], v[44:45] op_sel_hi:[1,0]
	s_nop 0
	v_addc_co_u32_e32 v165, vcc, 0, v165, vcc
	global_store_dwordx4 v[164:165], v[160:163], off
	v_pk_mul_f32 v[166:167], v[10:11], v[166:167]
	v_fmac_f32_e32 v27, v63, v41
	v_pk_mul_f32 v[160:161], v[34:35], v[44:45] op_sel_hi:[1,0]
	v_pk_mul_f32 v[162:163], v[32:33], v[44:45] op_sel_hi:[1,0]
	v_pk_mul_f32 v[160:161], v[12:13], v[160:161]
	v_pk_mul_f32 v[162:163], v[14:15], v[162:163]
	v_cvt_pk_bf16_f32 v160, v160, v161
	v_cvt_pk_bf16_f32 v161, v162, v163
	v_pk_mul_f32 v[162:163], v[30:31], v[44:45] op_sel_hi:[1,0]
	v_fmac_f32_e32 v27, v69, v38
	v_pk_mul_f32 v[162:163], v[8:9], v[162:163]
	v_fmac_f32_e32 v27, v75, v39
	v_cvt_pk_bf16_f32 v162, v162, v163
	v_cvt_pk_bf16_f32 v163, v166, v167
	global_store_dwordx4 v[164:165], v[160:163], off offset:1024
	v_fma_f32 v165, v48, v42, 0
	v_fma_f32 v167, v49, v42, 0
	v_fma_f32 v161, v46, v42, 0
	v_fma_f32 v163, v47, v42, 0
	v_fma_f32 v42, v50, v42, 0
	v_fmac_f32_e32 v161, v52, v43
	v_fmac_f32_e32 v163, v53, v43
	v_fmac_f32_e32 v165, v54, v43
	v_fmac_f32_e32 v167, v55, v43
	v_fmac_f32_e32 v42, v56, v43
	v_fmac_f32_e32 v161, v58, v40
	v_fmac_f32_e32 v163, v59, v40
	v_fmac_f32_e32 v165, v60, v40
	v_fmac_f32_e32 v167, v61, v40
	v_fmac_f32_e32 v42, v62, v40
	v_fmac_f32_e32 v161, v64, v41
	v_fmac_f32_e32 v163, v65, v41
	v_fmac_f32_e32 v165, v66, v41
	v_fmac_f32_e32 v167, v67, v41
	v_fmac_f32_e32 v42, v68, v41
	v_fmac_f32_e32 v161, v70, v38
	v_fmac_f32_e32 v163, v71, v38
	v_fmac_f32_e32 v165, v72, v38
	v_fmac_f32_e32 v167, v73, v38
	v_fmac_f32_e32 v42, v74, v38
	v_fmac_f32_e32 v161, v76, v39
	v_fmac_f32_e32 v163, v77, v39
	v_fmac_f32_e32 v165, v78, v39
	v_fmac_f32_e32 v167, v79, v39
	v_fmac_f32_e32 v42, v80, v39
	v_fmac_f32_e32 v27, v81, v36
	v_fmac_f32_e32 v161, v82, v36
	v_fmac_f32_e32 v163, v83, v36
	v_fmac_f32_e32 v165, v84, v36
	v_fmac_f32_e32 v167, v85, v36
	v_fmac_f32_e32 v42, v86, v36
	v_fmac_f32_e32 v27, v87, v37
	v_fmac_f32_e32 v161, v88, v37
	v_fmac_f32_e32 v163, v89, v37
	v_fmac_f32_e32 v165, v90, v37
	v_fmac_f32_e32 v167, v91, v37
	v_fmac_f32_e32 v42, v92, v37
	v_fmac_f32_e32 v27, v93, v34
	v_fmac_f32_e32 v161, v94, v34
	v_fmac_f32_e32 v163, v95, v34
	v_fmac_f32_e32 v165, v96, v34
	v_fmac_f32_e32 v167, v97, v34
	v_fmac_f32_e32 v42, v98, v34
	v_fmac_f32_e32 v27, v99, v35
	v_fmac_f32_e32 v161, v100, v35
	v_fmac_f32_e32 v163, v101, v35
	v_fmac_f32_e32 v165, v102, v35
	v_fmac_f32_e32 v167, v103, v35
	v_fmac_f32_e32 v42, v104, v35
	v_fmac_f32_e32 v27, v105, v32
	v_fmac_f32_e32 v161, v106, v32
	v_fmac_f32_e32 v163, v107, v32
	v_fmac_f32_e32 v165, v108, v32
	v_fmac_f32_e32 v167, v109, v32
	v_fmac_f32_e32 v42, v110, v32
	v_fmac_f32_e32 v27, v111, v33
	v_fmac_f32_e32 v161, v112, v33
	v_fmac_f32_e32 v163, v113, v33
	v_fmac_f32_e32 v165, v114, v33
	v_fmac_f32_e32 v167, v115, v33
	v_fmac_f32_e32 v42, v116, v33
	v_fmac_f32_e32 v27, v117, v30
	v_fmac_f32_e32 v161, v118, v30
	v_fmac_f32_e32 v163, v119, v30
	v_fmac_f32_e32 v165, v120, v30
	v_fmac_f32_e32 v167, v121, v30
	v_fmac_f32_e32 v42, v122, v30
	v_fmac_f32_e32 v27, v123, v31
	v_fmac_f32_e32 v161, v124, v31
	v_fmac_f32_e32 v163, v125, v31
	v_fmac_f32_e32 v165, v126, v31
	v_fmac_f32_e32 v167, v127, v31
	v_fmac_f32_e32 v42, v128, v31
	v_fmac_f32_e32 v27, v129, v28
	v_fmac_f32_e32 v161, v130, v28
	v_fmac_f32_e32 v163, v131, v28
	v_fmac_f32_e32 v165, v132, v28
	v_fmac_f32_e32 v167, v133, v28
	v_fmac_f32_e32 v42, v134, v28
	v_fmac_f32_e32 v27, v135, v29
	v_fmac_f32_e32 v161, v136, v29
	v_fmac_f32_e32 v163, v137, v29
	v_fmac_f32_e32 v165, v138, v29
	v_fmac_f32_e32 v167, v139, v29
	v_fmac_f32_e32 v42, v140, v29
	v_add_f32_dpp v27, v27, v27 quad_perm:[1,0,3,2] row_mask:0xf bank_mask:0xf bound_ctrl:1
	v_add_f32_dpp v161, v161, v161 quad_perm:[1,0,3,2] row_mask:0xf bank_mask:0xf bound_ctrl:1
; __device__ __forceinline__ float wave_sum(float v) { return xor32_sum(xor16_sum(row16_sum(v))); }
; template <bool FG, bool BIN = false> __device__ __forceinline__ void norm_phase(const float* hin, const float* gain, bf16_t* out, const float* win, const float* fbias, float* logf, int gw, int NGW, int lane) {
;     ...
;         if (FG) {
;             float mine = 0.f;
; #pragma unroll
;             for (int j = 0; j < 6; ++j) { float d = 0.f;
; #pragma unroll
;                 for (int e = 0; e < 16; ++e) d += x[e] * wf[j][e];
;                 d = wave_sum(d) * rstd + fb[j];
;                 if (lane == j) mine = d; }
;             if (lane < 6) { const float v = mine; logf[(size_t)row * 6 + lane] = fminf(v, 0.f) - log1pf(expf(-fabsf(v))); }
	v_add_f32_dpp v163, v163, v163 quad_perm:[1,0,3,2] row_mask:0xf bank_mask:0xf bound_ctrl:1
	v_add_f32_dpp v165, v165, v165 quad_perm:[1,0,3,2] row_mask:0xf bank_mask:0xf bound_ctrl:1
	v_add_f32_dpp v167, v167, v167 quad_perm:[1,0,3,2] row_mask:0xf bank_mask:0xf bound_ctrl:1
	v_add_f32_dpp v28, v42, v42 quad_perm:[1,0,3,2] row_mask:0xf bank_mask:0xf bound_ctrl:1
	v_add_f32_dpp v27, v27, v27 quad_perm:[2,3,0,1] row_mask:0xf bank_mask:0xf bound_ctrl:1
	v_add_f32_dpp v161, v161, v161 quad_perm:[2,3,0,1] row_mask:0xf bank_mask:0xf bound_ctrl:1
	v_add_f32_dpp v163, v163, v163 quad_perm:[2,3,0,1] row_mask:0xf bank_mask:0xf bound_ctrl:1
	v_add_f32_dpp v165, v165, v165 quad_perm:[2,3,0,1] row_mask:0xf bank_mask:0xf bound_ctrl:1
	v_add_f32_dpp v167, v167, v167 quad_perm:[2,3,0,1] row_mask:0xf bank_mask:0xf bound_ctrl:1
	v_add_f32_dpp v28, v28, v28 quad_perm:[2,3,0,1] row_mask:0xf bank_mask:0xf bound_ctrl:1
	v_add_f32_dpp v27, v27, v27 row_half_mirror row_mask:0xf bank_mask:0xf bound_ctrl:1
	v_add_f32_dpp v161, v161, v161 row_half_mirror row_mask:0xf bank_mask:0xf bound_ctrl:1
	v_add_f32_dpp v163, v163, v163 row_half_mirror row_mask:0xf bank_mask:0xf bound_ctrl:1
	v_add_f32_dpp v165, v165, v165 row_half_mirror row_mask:0xf bank_mask:0xf bound_ctrl:1
	v_add_f32_dpp v167, v167, v167 row_half_mirror row_mask:0xf bank_mask:0xf bound_ctrl:1
	v_add_f32_dpp v28, v28, v28 row_half_mirror row_mask:0xf bank_mask:0xf bound_ctrl:1
	v_add_f32_dpp v27, v27, v27 row_mirror row_mask:0xf bank_mask:0xf bound_ctrl:1
	v_add_f32_dpp v161, v161, v161 row_mirror row_mask:0xf bank_mask:0xf bound_ctrl:1
	v_add_f32_dpp v163, v163, v163 row_mirror row_mask:0xf bank_mask:0xf bound_ctrl:1
	v_add_f32_dpp v165, v165, v165 row_mirror row_mask:0xf bank_mask:0xf bound_ctrl:1
	v_add_f32_dpp v167, v167, v167 row_mirror row_mask:0xf bank_mask:0xf bound_ctrl:1
	v_add_f32_dpp v28, v28, v28 row_mirror row_mask:0xf bank_mask:0xf bound_ctrl:1
	v_mov_b32_e32 v160, v27
	v_mov_b32_e32 v162, v161
	v_mov_b32_e32 v164, v163
	v_mov_b32_e32 v166, v165
	v_mov_b32_e32 v168, v167
	v_mov_b32_e32 v29, v28
	v_permlane16_swap_b32_e32 v27, v160
	v_permlane16_swap_b32_e32 v161, v162
	v_permlane16_swap_b32_e32 v163, v164
	v_permlane16_swap_b32_e32 v165, v166
	v_permlane16_swap_b32_e32 v167, v168
	v_permlane16_swap_b32_e32 v28, v29
	v_add_f32_e32 v27, v27, v160
	v_add_f32_e32 v161, v161, v162
	v_add_f32_e32 v163, v163, v164
	v_add_f32_e32 v165, v165, v166
	v_add_f32_e32 v167, v167, v168
	v_add_f32_e32 v28, v28, v29
	v_mov_b32_e32 v160, v27
	v_mov_b32_e32 v162, v161
	v_mov_b32_e32 v164, v163
	v_mov_b32_e32 v166, v165
	v_mov_b32_e32 v168, v167
	v_mov_b32_e32 v29, v28
	v_permlane32_swap_b32_e32 v27, v160
	v_permlane32_swap_b32_e32 v161, v162
	v_permlane32_swap_b32_e32 v163, v164
	v_permlane32_swap_b32_e32 v165, v166
	v_permlane32_swap_b32_e32 v167, v168
	v_permlane32_swap_b32_e32 v28, v29
	s_and_saveexec_b64 s[0:1], s[10:11]
	s_cbranch_execz .LBB0_1107
; __device__ __forceinline__ float wave_sum(float v) { return xor32_sum(xor16_sum(row16_sum(v))); }
; template <bool FG, bool BIN = false> __device__ __forceinline__ void norm_phase(const float* hin, const float* gain, bf16_t* out, const float* win, const float* fbias, float* logf, int gw, int NGW, int lane) {
;     ...
;             for (int j = 0; j < 6; ++j) { float d = 0.f;
; #pragma unroll
;                 for (int e = 0; e < 16; ++e) d += x[e] * wf[j][e];
;                 d = wave_sum(d) * rstd + fb[j];
;                 if (lane == j) mine = d; }
;             if (lane < 6) { const float v = mine; logf[(size_t)row * 6 + lane] = fminf(v, 0.f) - log1pf(expf(-fabsf(v))); }
	v_add_f32_e32 v27, v27, v160
	v_add_f32_e32 v32, v161, v162
	v_fma_f32 v27, v44, v27, v16
	v_add_f32_e32 v31, v163, v164
	v_fma_f32 v32, v44, v32, v17
	v_cndmask_b32_e64 v27, 0, v27, s[12:13]
	v_add_f32_e32 v30, v165, v166
	v_fma_f32 v31, v44, v31, v18
	v_cndmask_b32_e64 v27, v27, v32, s[14:15]
	v_add_f32_e32 v28, v28, v29
	v_add_f32_e32 v29, v167, v168
	v_fma_f32 v30, v44, v30, v19
	v_cndmask_b32_e64 v27, v27, v31, s[16:17]
	v_fma_f32 v29, v44, v29, v22
	v_cndmask_b32_e64 v27, v27, v30, s[18:19]
	v_fma_f32 v28, v44, v28, v23
	v_cndmask_b32_e64 v27, v27, v29, s[20:21]
	v_cndmask_b32_e64 v27, v27, v28, s[22:23]
	v_mul_f32_e64 v28, |v27|, s26
	v_fma_f32 v29, |v27|, s26, -v28
	v_rndne_f32_e32 v30, v28
	v_fma_f32 v29, |v27|, s27, v29
	v_sub_f32_e32 v28, v28, v30
	v_add_f32_e32 v28, v28, v29
	v_exp_f32_e32 v28, v28
	v_cvt_i32_f32_e32 v29, v30
	v_cmp_ngt_f32_e64 vcc, |v27|, s28
	v_max_f32_e32 v30, v27, v27
	v_min_f32_e32 v42, 0, v30
	v_ldexp_f32 v28, v28, v29
	v_cndmask_b32_e32 v28, 0, v28, vcc
	v_cmp_nlt_f32_e64 vcc, |v27|, s29
	s_nop 1
	v_cndmask_b32_e32 v43, v143, v28, vcc
	v_add_f32_e32 v27, 1.0, v43
	v_add_f32_e32 v28, -1.0, v27
	v_sub_f32_e32 v29, v28, v27
	v_add_f32_e32 v29, 1.0, v29
	v_sub_f32_e32 v28, v43, v28
	v_add_f32_e32 v30, v28, v29
	v_frexp_mant_f32_e32 v31, v27
	v_cvt_f64_f32_e32 v[28:29], v27
	v_frexp_exp_i32_f64_e32 v28, v[28:29]
	v_cmp_gt_f32_e32 vcc, s31, v31
	s_nop 1
	v_subbrev_co_u32_e32 v36, vcc, 0, v28, vcc
	v_sub_u32_e32 v28, 0, v36
	v_ldexp_f32 v27, v27, v28
	v_ldexp_f32 v28, v30, v28
	v_add_f32_e32 v30, -1.0, v27
	v_add_f32_e32 v29, 1.0, v30
	v_sub_f32_e32 v29, v27, v29
	v_add_f32_e32 v31, v28, v29
	v_add_f32_e32 v29, 1.0, v27
	v_add_f32_e32 v32, -1.0, v29
	v_sub_f32_e32 v27, v27, v32
	v_add_f32_e32 v27, v28, v27
	v_add_f32_e32 v37, v29, v27
	v_rcp_f32_e32 v38, v37
	v_sub_f32_e32 v28, v29, v37
	v_add_f32_e32 v29, v30, v31
	v_add_f32_e32 v27, v27, v28
	v_mul_f32_e32 v40, v29, v38
	v_sub_f32_e32 v28, v30, v29
	v_mul_f32_e32 v30, v37, v40
	v_fma_f32 v32, v40, v37, -v30
	v_fmac_f32_e32 v32, v40, v27
	v_add_f32_e32 v39, v31, v28
	v_add_f32_e32 v28, v30, v32
	v_sub_f32_e32 v31, v29, v28
	v_pk_add_f32 v[34:35], v[28:29], v[30:31] neg_lo:[0,1] neg_hi:[0,1]
	v_mov_b32_e32 v33, v28
	v_pk_add_f32 v[28:29], v[34:35], v[32:33] neg_lo:[0,1] neg_hi:[0,1]
	v_cmp_neq_f32_e32 vcc, s30, v43
	v_add_f32_e32 v29, v39, v29
	v_add_f32_e32 v28, v28, v29
	v_add_f32_e32 v29, v31, v28
	v_mul_f32_e32 v39, v38, v29
	v_mul_f32_e32 v30, v37, v39
	v_fma_f32 v32, v39, v37, -v30
	v_fmac_f32_e32 v32, v39, v27
	v_sub_f32_e32 v27, v31, v29
	v_add_f32_e32 v27, v28, v27
	v_add_f32_e32 v28, v30, v32
	v_sub_f32_e32 v31, v29, v28
	v_pk_add_f32 v[34:35], v[28:29], v[30:31] neg_lo:[0,1] neg_hi:[0,1]
	v_mov_b32_e32 v33, v28
	v_pk_add_f32 v[28:29], v[34:35], v[32:33] neg_lo:[0,1] neg_hi:[0,1]
	s_nop 0
	v_add_f32_e32 v27, v27, v29
	v_add_f32_e32 v27, v28, v27
	v_add_f32_e32 v29, v40, v39
	v_add_f32_e32 v27, v31, v27
	v_sub_f32_e32 v28, v29, v40
	v_mul_f32_e32 v27, v38, v27
	v_sub_f32_e32 v28, v39, v28
	v_add_f32_e32 v30, v28, v27
	v_add_f32_e32 v32, v29, v30
	v_cvt_f32_i32_e32 v28, v36
	v_mul_f32_e32 v33, v32, v32
	v_sub_f32_e32 v29, v32, v29
	v_fmamk_f32 v27, v33, 0x3e9b6dac, v142
	v_sub_f32_e32 v29, v30, v29
	v_fmaak_f32 v27, v33, v27, 0x3f2aaada
	v_ldexp_f32 v34, v29, 1
	v_mul_f32_e32 v29, v32, v33
	v_ldexp_f32 v31, v32, 1
	v_pk_mul_f32 v[32:33], v[28:29], v[26:27]
	s_nop 0
	v_fma_f32 v30, v28, s33, -v32
	v_fmac_f32_e32 v30, 0xb102e308, v28
	v_pk_add_f32 v[28:29], v[32:33], v[30:31]
	s_nop 0
	v_sub_f32_e32 v27, v29, v31
	v_sub_f32_e32 v27, v33, v27
	v_add_f32_e32 v35, v34, v27
	v_mov_b32_e32 v34, v32
	v_pk_add_f32 v[32:33], v[28:29], v[32:33] neg_lo:[0,1] neg_hi:[0,1]
	v_pk_add_f32 v[36:37], v[28:29], v[34:35]
	v_mov_b32_e32 v31, v28
	v_mov_b32_e32 v33, v37
	v_pk_add_f32 v[38:39], v[30:31], v[32:33] neg_lo:[0,1] neg_hi:[0,1]
	v_pk_add_f32 v[30:31], v[30:31], v[32:33]
	v_mov_b32_e32 v34, v35
	v_pk_add_f32 v[32:33], v[30:31], v[28:29] op_sel:[1,0] op_sel_hi:[0,1] neg_lo:[0,1] neg_hi:[0,1]
	v_pk_add_f32 v[40:41], v[36:37], v[32:33] op_sel_hi:[1,0] neg_lo:[0,1] neg_hi:[0,1]
	v_mov_b32_e32 v36, v37
	v_mov_b32_e32 v37, v31
	v_pk_mov_b32 v[32:33], v[28:29], v[32:33] op_sel:[1,0]
	v_mov_b32_e32 v35, v28
	v_pk_add_f32 v[32:33], v[36:37], v[32:33] neg_lo:[0,1] neg_hi:[0,1]
	v_mov_b32_e32 v40, v38
	v_pk_add_f32 v[28:29], v[34:35], v[32:33] neg_lo:[0,1] neg_hi:[0,1]
	v_mov_b32_e32 v39, v31
	v_pk_add_f32 v[32:33], v[40:41], v[28:29]
	s_nop 0
	v_pk_add_f32 v[34:35], v[32:33], v[32:33] op_sel:[0,1] op_sel_hi:[1,0]
	s_nop 0
	v_pk_add_f32 v[30:31], v[30:31], v[34:35] op_sel:[1,0] op_sel_hi:[0,1]
	v_mov_b32_e32 v33, v30
	v_pk_add_f32 v[36:37], v[32:33], v[38:39] neg_lo:[0,1] neg_hi:[0,1]
	v_mov_b32_e32 v29, v34
	v_sub_f32_e32 v27, v32, v36
	v_pk_add_f32 v[28:29], v[28:29], v[36:37] neg_lo:[0,1] neg_hi:[0,1]
	v_sub_f32_e32 v27, v38, v27
	v_add_f32_e32 v27, v28, v27
	v_add_f32_e32 v27, v27, v29
	v_add_f32_e32 v27, v30, v27
	v_cndmask_b32_e32 v27, v143, v27, vcc
	v_cmp_lt_f32_e64 vcc, |v43|, s34
	s_nop 1
	v_cndmask_b32_e32 v27, v27, v43, vcc
	v_sub_f32_e32 v27, v42, v27
	global_store_dword v[24:25], v27, off
	s_branch .LBB0_1107
